# speedup vs baseline: 1.0151x; 1.0080x over previous
; #define otid() otid_(wid_s_)
; #define SLOAD(k0) do { SLOAD_KR(k0); SLOAD_V(k0); } while (0)
; #define SWRITE(b) do { SWRITE_KR(b); SWRITE_V(b); } while (0)
; #define SWAIT() asm volatile("s_waitcnt vmcnt(0)" ::: "memory")
; DEVI void attn_item(const u16* __restrict__ Qb, const u16* __restrict__ KNh, const u16* __restrict__ VTh, int Lpad, const u16* __restrict__ KRb,
;                     const u16* __restrict__ SZb, u16* __restrict__ AOb, int NT, char* lds, const int wid_s_) {
;   const int tid = otid(), wid = tid >> 6, lane = tid & 63, r32 = lane & 31, hi = lane >> 5;
;   char* V_lds = lds; char* K_lds = lds + 2 * SHM_V; char* R_lds = lds + 2 * SHM_V + 2 * SHM_K;
;   char* Qrs = lds + 2 * SHM_V + 2 * SHM_K + 2 * SHM_R + wid * 4096;
;   float* wsf = (float*)(lds + 2 * SHM_V + 2 * SHM_K + 2 * SHM_R + 32768) + wid * 64; float* li_l = wsf; float* al_l = wsf + 32;
;   float m_reg = -1e30f, l_reg = 0; f32x16 o[4] = {}; bf16x8 qr[8];
;   const u16* Qw = Qb + (size_t)(wid * 32 + r32) * LDQ + hi * 8;
; #pragma unroll
;   for (int d0 = 0; d0 < 8; ++d0) qr[d0] = __builtin_nontemporal_load(reinterpret_cast<const bf16x8*>(Qw + d0 * 16));
; #pragma unroll
;   for (int d0 = 0; d0 < 4; ++d0) *reinterpret_cast<bf16x8*>(Qrs + RSWZ(r32, (d0 * 16 + hi * 8) * 2)) = *reinterpret_cast<const bf16x8*>(Qw + 128 + d0 * 16);
;   const int sr = tid >> 4, sc = (tid & 15) * 8;
;   const int vd = tid >> 3, vc = tid & 7;
;   const int rr_ = tid >> 3, rc_ = (tid & 7) * 8;
;   bf16x8 vs0, vs1, ks0, ks1, rs0;
;   const unsigned vo_k = (unsigned)((sr * LDK + sc) * 2), vo_r = (unsigned)((rr_ * 64 + rc_) * 2), vo_v = (unsigned)((vd * Lpad + vc * 8) * 2);
;   const size_t vhalf = (size_t)64 * Lpad * 2;
;     ...
;   f32x16 pA0, pA1, pB0, pB1; float mnA, mnB, alA, alB; bf16x8 pa0, pa1, pa2, pa3;
;   SLOAD(0); SWAIT(); SWRITE(0); __syncthreads();
.LBB0_980:
	s_lshr_b32 s2, s1, s93
	s_and_b32 s46, s1, s31
	s_lshr_b32 s8, s2, 4
	s_and_b32 s1, s2, 15
	s_mul_i32 s13, s8, s29
	s_lshl_b64 s[6:7], s[46:47], 8
	s_mul_hi_u32 s9, s8, s29
	s_add_u32 s56, s13, s6
	s_addc_u32 s57, s9, s7
	s_mul_i32 s6, s57, 0x1800
	s_mul_hi_u32 s7, s56, 0x1800
	s_add_i32 s7, s7, s6
	s_mul_i32 s6, s56, 0x1800
	s_add_u32 s6, s94, s6
	s_addc_u32 s7, s95, s7
	s_mul_i32 s9, s1, 0x180
	s_add_u32 s14, s6, s9
	s_mul_hi_u32 s17, s8, s28
	s_mul_i32 s16, s8, s28
	s_addc_u32 s15, s7, 0
	s_lshl_b64 s[8:9], s[16:17], 12
	s_add_u32 s6, s52, s8
	v_mov_b32_e32 v51, v207
	s_addc_u32 s7, s53, s9
	s_lshl_b32 s35, s1, 7
	s_lshl_b32 s1, s1, 8
	s_add_u32 s18, s6, s1
	v_ashrrev_i32_e32 v40, 6, v51
	v_and_b32_e32 v176, 31, v51
	v_lshlrev_b32_e32 v175, 5, v40
	s_addc_u32 s19, s7, 0
	s_lshl_b32 s46, s2, 7
	v_bfe_u32 v174, v51, 5, 1
	v_or_b32_e32 v2, v175, v176
	v_mov_b64_e32 v[0:1], s[14:15]
	v_lshlrev_b32_e32 v42, 4, v51
	s_mul_hi_u32 s7, s46, s28
	s_mul_i32 s6, s46, s28
	v_mad_i64_i32 v[0:1], s[14:15], v2, s89, v[0:1]
	v_lshlrev_b32_e32 v160, 4, v174
	v_mov_b32_e32 v161, v205
	v_ashrrev_i32_e32 v41, 4, v51
	v_and_b32_e32 v49, 0xf0, v42
	v_ashrrev_i32_e32 v16, 3, v51
	s_lshl_b64 s[6:7], s[6:7], 1
	v_lshl_add_u64 v[38:39], v[0:1], 0, v[160:161]
	v_lshl_or_b32 v204, v41, 12, v49
	v_lshlrev_b32_e32 v43, 7, v16
	v_and_b32_e32 v17, 0x70, v42
	v_mul_lo_u32 v16, s5, v16
	s_add_u32 s6, s70, s6
	global_load_dwordx4 v[0:3], v[38:39], off offset:256
	global_load_dwordx4 v[4:7], v[38:39], off offset:288
	global_load_dwordx4 v[8:11], v[38:39], off offset:320
	global_load_dwordx4 v[12:15], v[38:39], off offset:352
	v_or_b32_e32 v48, v43, v17
	v_or_b32_e32 v50, v17, v16
	v_lshl_add_u64 v[16:17], s[18:19], 0, v[204:205]
	s_mov_b32 s2, 0x20000
	s_addc_u32 s7, s71, s7
	s_lshl_b64 s[58:59], s[16:17], 7
	v_add_co_u32_e32 v22, vcc, s2, v16
	s_add_u32 s16, s44, s58
	s_nop 0
	v_addc_co_u32_e32 v23, vcc, 0, v17, vcc
	s_addc_u32 s17, s45, s59
	global_load_dwordx4 v[18:21], v204, s[18:19]
	s_nop 0
	global_load_dwordx4 v[22:25], v[22:23], off
	s_nop 0
	global_load_dwordx4 v[26:29], v48, s[16:17]
	s_add_u32 s14, s6, s54
	s_addc_u32 s15, s7, 0
	global_load_dwordx4 v[30:33], v50, s[6:7]
	global_load_dwordx4 v[34:37], v50, s[14:15]
	global_load_dwordx4 v[96:99], v[38:39], off nt
	global_load_dwordx4 v[100:103], v[38:39], off offset:32 nt
	global_load_dwordx4 v[104:107], v[38:39], off offset:64 nt
	global_load_dwordx4 v[108:111], v[38:39], off offset:96 nt
	global_load_dwordx4 v[112:115], v[38:39], off offset:128 nt
	global_load_dwordx4 v[116:119], v[38:39], off offset:160 nt
	global_load_dwordx4 v[120:123], v[38:39], off offset:192 nt
	global_load_dwordx4 v[124:127], v[38:39], off offset:224 nt
	v_mov_b32_e32 v45, 0x14000
	v_lshlrev_b32_e32 v44, 3, v51
	v_lshl_add_u32 v183, v40, 12, v45
	v_lshlrev_b32_e32 v72, 7, v176
	v_and_b32_e32 v73, 0x70, v44
	v_or_b32_e32 v40, v183, v72
	v_bitop3_b32 v44, v160, v44, s90 bitop3:0x78
	v_bitop3_b32 v45, v160, v73, 32 bitop3:0x36
	v_bitop3_b32 v46, v160, v73, 64 bitop3:0x36
	v_or_b32_e32 v44, v40, v44
	v_or_b32_e32 v45, v40, v45
	s_movk_i32 s2, 0x60
	v_or_b32_e32 v74, 64, v160
	v_or_b32_e32 v75, 0x60, v160
	v_bitop3_b32 v177, v160, v72, v73 bitop3:0xde
	v_or_b32_e32 v195, 0x10000, v177
	v_or_b32_e32 v196, 0x11000, v177
	v_bitop3_b32 v180, v74, v72, v73 bitop3:0xde
	v_or_b32_e32 v199, 0x10000, v180
	v_or_b32_e32 v200, 0x11000, v180
	s_waitcnt vmcnt(16)
	ds_write_b128 v44, v[0:3]
	s_waitcnt vmcnt(15)
	ds_write_b128 v45, v[4:7]
	v_or_b32_e32 v0, v40, v46
	s_waitcnt vmcnt(14)
	ds_write_b128 v0, v[8:11]
	v_bitop3_b32 v0, v160, v73, s2 bitop3:0x36
	v_or_b32_e32 v0, v40, v0
	v_xor_b32_e32 v1, v42, v51
	s_waitcnt vmcnt(13)
	ds_write_b128 v0, v[12:15]
	v_lshlrev_b32_e32 v0, 8, v41
	s_movk_i32 s2, 0xf0
	v_and_or_b32 v185, v1, s90, v43
	v_and_or_b32 v184, v1, s2, v0
	v_add_u32_e32 v186, 0x10000, v185
	s_waitcnt vmcnt(0)
	s_waitcnt vmcnt(12)
	ds_write_b128 v184, v[18:21] offset:32768
	s_waitcnt vmcnt(11)
	ds_write_b128 v184, v[22:25] offset:40960
	s_waitcnt vmcnt(10)
	ds_write_b128 v186, v[26:29]
	s_waitcnt vmcnt(9)
	ds_write_b128 v185, v[30:33]
	s_waitcnt vmcnt(8)
	ds_write_b128 v185, v[34:37] offset:8192
	v_lshlrev_b32_e32 v26, 8, v176
	v_bitop3_b32 v187, v160, v26, v49 bitop3:0xde
	s_waitcnt lgkmcnt(0)
	s_barrier
; #define SLOAD(k0) do { SLOAD_KR(k0); SLOAD_V(k0); } while (0)
; #define SWRITE(b) do { SWRITE_KR(b); SWRITE_V(b); } while (0)
; #define SWAIT() asm volatile("s_waitcnt vmcnt(0)" ::: "memory")
; DEVI void qkt(f32x16& p0, f32x16& p1, const char* Ks, const char* Rs, const bf16x8* qr, const char* Qrs, int r32, int hi) {
;   p0 = f32x16{}; p1 = f32x16{};
; #pragma unroll
;   for (int d0 = 0; d0 < 8; ++d0) { int cb = (d0 * 16 + hi * 8) * 2;
;     bf16x8 b0 = *reinterpret_cast<const bf16x8*>(Ks + KSWZ(r32, cb));
;     bf16x8 b1 = *reinterpret_cast<const bf16x8*>(Ks + KSWZ(32 + r32, cb));
;     p0 = __builtin_amdgcn_mfma_f32_32x32x16_bf16(b0, qr[d0], p0, 0, 0, 0);
;     p1 = __builtin_amdgcn_mfma_f32_32x32x16_bf16(b1, qr[d0], p1, 0, 0, 0); }
; #pragma unroll
;   for (int d0 = 0; d0 < 4; ++d0) { int cb = (d0 * 16 + hi * 8) * 2;
;     bf16x8 b0 = *reinterpret_cast<const bf16x8*>(Rs + RSWZ(r32, cb));
;     bf16x8 b1 = *reinterpret_cast<const bf16x8*>(Rs + RSWZ(32 + r32, cb));
;     bf16x8 qf = *reinterpret_cast<const bf16x8*>(Qrs + RSWZ(r32, cb));
;     p0 = __builtin_amdgcn_mfma_f32_32x32x16_bf16(b0, qf, p0, 0, 0, 0);
;     p1 = __builtin_amdgcn_mfma_f32_32x32x16_bf16(b1, qf, p1, 0, 0, 0); }
; }
; DEVI void attn_item(const u16* __restrict__ Qb, const u16* __restrict__ KNh, const u16* __restrict__ VTh, int Lpad, const u16* __restrict__ KRb,
;                     const u16* __restrict__ SZb, u16* __restrict__ AOb, int NT, char* lds, const int wid_s_) {
;     ...
;   SLOAD(0); SWAIT(); SWRITE(0); __syncthreads();
;   qkt(pA0, pA1, K_lds, R_lds, qr, Qrs, r32, hi); partialSM(pA0, pA1, m_reg, mnA, alA);
;   SLOAD(64);
;   SWAIT(); SWRITE(1); __syncthreads();
	ds_read_b128 v[0:3], v187 offset:32768
	ds_read_b128 v[18:21], v187 offset:40960
	s_waitcnt vmcnt(7) lgkmcnt(1)
	v_mfma_f32_32x32x16_bf16 v[0:15], v[0:3], v[96:99], 0
	v_or_b32_e32 v27, 32, v160
	v_bitop3_b32 v188, v27, v26, v49 bitop3:0xde
	v_bitop3_b32 v189, v74, v26, v49 bitop3:0xde
	v_bitop3_b32 v190, v75, v26, v49 bitop3:0xde
	v_bitop3_b32 v161, v27, v72, v73 bitop3:0xde
	v_or_b32_e32 v197, 0x10000, v161
	s_mov_b32 s2, 0x40000
	s_waitcnt lgkmcnt(0)
	v_mfma_f32_32x32x16_bf16 v[32:47], v[18:21], v[96:99], 0
	ds_read_b128 v[18:21], v188 offset:32768
	ds_read_b128 v[22:25], v188 offset:40960
	v_or_b32_e32 v198, 0x11000, v161
	v_bitop3_b32 v179, v75, v72, v73 bitop3:0xde
	v_or_b32_e32 v201, 0x10000, v179
	v_or_b32_e32 v202, 0x11000, v179
	v_add_u32_e32 v203, 0x12000, v185
	s_mov_b32 s26, s12
	s_waitcnt vmcnt(6) lgkmcnt(1)
	v_mfma_f32_32x32x16_bf16 v[0:15], v[18:21], v[100:103], v[0:15]
	s_mov_b32 s27, s12
	s_mov_b32 s13, s12
	s_mov_b32 s18, s12
	s_mov_b32 s19, s12
	s_mov_b32 s20, s12
	s_mov_b32 s21, s12
	s_mov_b32 s22, s12
	s_waitcnt lgkmcnt(0)
	v_mfma_f32_32x32x16_bf16 v[32:47], v[22:25], v[100:103], v[32:47]
	ds_read_b128 v[18:21], v189 offset:32768
	ds_read_b128 v[22:25], v189 offset:40960
	s_mov_b32 s23, s12
	s_mov_b32 s24, s12
	s_mov_b32 s25, s12
	v_mov_b32_e32 v182, 0
	s_waitcnt vmcnt(5) lgkmcnt(1)
	v_mfma_f32_32x32x16_bf16 v[0:15], v[18:21], v[104:107], v[0:15]
	s_waitcnt lgkmcnt(0)
	v_mfma_f32_32x32x16_bf16 v[32:47], v[22:25], v[104:107], v[32:47]
	ds_read_b128 v[18:21], v190 offset:32768
	ds_read_b128 v[22:25], v190 offset:40960
	s_waitcnt vmcnt(4) lgkmcnt(1)
	v_mfma_f32_32x32x16_bf16 v[0:15], v[18:21], v[108:111], v[0:15]
	v_or_b32_e32 v18, 0x80, v160
	v_bitop3_b32 v191, v18, v26, v49 bitop3:0xde
	s_waitcnt lgkmcnt(0)
	v_mfma_f32_32x32x16_bf16 v[32:47], v[22:25], v[108:111], v[32:47]
	ds_read_b128 v[18:21], v191 offset:32768
	ds_read_b128 v[22:25], v191 offset:40960
	s_waitcnt vmcnt(3) lgkmcnt(1)
	v_mfma_f32_32x32x16_bf16 v[0:15], v[18:21], v[112:115], v[0:15]
	v_or_b32_e32 v18, 0xa0, v160
	v_bitop3_b32 v192, v18, v26, v49 bitop3:0xde
	s_waitcnt lgkmcnt(0)
	v_mfma_f32_32x32x16_bf16 v[32:47], v[22:25], v[112:115], v[32:47]
	ds_read_b128 v[18:21], v192 offset:32768
	ds_read_b128 v[22:25], v192 offset:40960
	s_waitcnt vmcnt(2) lgkmcnt(1)
	v_mfma_f32_32x32x16_bf16 v[0:15], v[18:21], v[116:119], v[0:15]
	v_or_b32_e32 v18, 0xc0, v160
	v_bitop3_b32 v193, v18, v26, v49 bitop3:0xde
	s_waitcnt lgkmcnt(0)
	v_mfma_f32_32x32x16_bf16 v[32:47], v[22:25], v[116:119], v[32:47]
	ds_read_b128 v[18:21], v193 offset:32768
	ds_read_b128 v[22:25], v193 offset:40960
	s_waitcnt vmcnt(1) lgkmcnt(1)
	v_mfma_f32_32x32x16_bf16 v[0:15], v[18:21], v[120:123], v[0:15]
	v_or_b32_e32 v18, 0xe0, v160
	v_bitop3_b32 v194, v18, v26, v49 bitop3:0xde
	v_mov_b32_e32 v49, v205
	v_lshl_add_u64 v[30:31], s[16:17], 0, v[48:49]
	s_mov_b32 s16, s12
	s_mov_b32 s17, s12
	v_lshl_add_u64 v[166:167], s[58:59], 0, v[48:49]
	v_add_u32_e32 v166, 0xa0e5000, v166
	s_waitcnt lgkmcnt(0)
	v_mfma_f32_32x32x16_bf16 v[32:47], v[22:25], v[120:123], v[32:47]
	ds_read_b128 v[18:21], v194 offset:32768
	ds_read_b128 v[22:25], v194 offset:40960
	s_waitcnt vmcnt(0) lgkmcnt(1)
	v_mfma_f32_32x32x16_bf16 v[0:15], v[18:21], v[124:127], v[0:15]
	ds_read_b128 v[18:21], v195
	s_waitcnt lgkmcnt(1)
	v_mfma_f32_32x32x16_bf16 v[32:47], v[22:25], v[124:127], v[32:47]
	v_or_b32_e32 v22, v183, v177
	ds_read_b128 v[22:25], v22
	ds_read_b128 v[26:29], v196
	ds_read_b128 v[52:55], v197
	s_waitcnt lgkmcnt(2)
	v_mfma_f32_32x32x16_bf16 v[0:15], v[18:21], v[22:25], v[0:15]
	v_or_b32_e32 v18, v183, v161
	ds_read_b128 v[18:21], v18
	s_waitcnt lgkmcnt(2)
	v_mfma_f32_32x32x16_bf16 v[32:47], v[26:29], v[22:25], v[32:47]
	v_add_co_u32_e32 v22, vcc, s2, v16
	s_mov_b32 s2, 0x60000
	s_nop 0
	v_addc_co_u32_e32 v23, vcc, 0, v17, vcc
	v_add_co_u32_e32 v16, vcc, s2, v16
	s_movk_i32 s2, 0x2000
	s_nop 0
	v_addc_co_u32_e32 v17, vcc, 0, v17, vcc
	global_load_dwordx4 v[56:59], v[22:23], off
	global_load_dwordx4 v[60:63], v[16:17], off
	v_add_co_u32_e32 v16, vcc, s2, v30
	s_waitcnt lgkmcnt(0)
	v_mfma_f32_32x32x16_bf16 v[0:15], v[52:55], v[18:21], v[0:15]
	v_addc_co_u32_e32 v17, vcc, 0, v31, vcc
	global_load_dwordx4 v[64:67], v[16:17], off
	global_load_dwordx4 v[68:71], v50, s[6:7] offset:128
	global_load_dwordx4 v[52:55], v50, s[14:15] offset:128
	ds_read_b128 v[22:25], v198
	ds_read_b128 v[26:29], v199
	v_or_b32_e32 v16, v183, v180
	s_waitcnt lgkmcnt(1)
	v_mfma_f32_32x32x16_bf16 v[32:47], v[22:25], v[18:21], v[32:47]
	ds_read_b128 v[16:19], v16
	ds_read_b128 v[20:23], v200
	ds_read_b128 v[72:75], v201
	v_and_b32_e32 v30, 0x3fffffc0, v51
	v_mov_b32_e32 v24, 0x1c000
	v_lshl_add_u32 v178, v30, 2, v24
	v_mov_b32_e32 v51, v205
	s_mov_b32 s14, s12
	s_waitcnt lgkmcnt(2)
	v_mfma_f32_32x32x16_bf16 v[0:15], v[26:29], v[16:19], v[0:15]
	s_mov_b32 s15, s12
	s_mov_b32 s2, 4
	v_cmp_eq_u32_e64 s[6:7], 0, v174
	v_lshl_or_b32 v181, v176, 2, v178
	s_waitcnt lgkmcnt(1)
	v_mfma_f32_32x32x16_bf16 v[32:47], v[20:23], v[16:19], v[32:47]
	v_or_b32_e32 v16, v183, v179
	ds_read_b128 v[76:79], v202
	ds_read_b128 v[80:83], v16
	s_waitcnt vmcnt(0)
	s_waitcnt vmcnt(4)
	ds_write_b128 v184, v[56:59] offset:49152
	s_waitcnt vmcnt(3)
	ds_write_b128 v184, v[60:63] offset:57344
	s_waitcnt lgkmcnt(2)
	v_mfma_f32_32x32x16_bf16 v[0:15], v[72:75], v[80:83], v[0:15]
	s_waitcnt vmcnt(2)
	ds_write_b128 v203, v[64:67]
	s_waitcnt vmcnt(1)
	ds_write_b128 v185, v[68:71] offset:16384
	s_waitcnt vmcnt(0)
; #define SLOAD(k0) do { SLOAD_KR(k0); SLOAD_V(k0); } while (0)
; DEVI void partialSM(f32x16& p0, f32x16& p1, float& m_reg, float& mn, float& alpha) {
;   constexpr float C = ASCALE * 1.4426950408889634f;
;   float pmax = p0[0];
; #pragma unroll
;   for (int r = 1; r < 16; ++r) pmax = fmaxf(pmax, p0[r]);
; #pragma unroll
;   for (int r = 0; r < 16; ++r) pmax = fmaxf(pmax, p1[r]);
;   { auto rr = __builtin_amdgcn_permlane32_swap(__float_as_uint(pmax), __float_as_uint(pmax), false, false);
;     pmax = fmaxf(__uint_as_float(rr[0]), __uint_as_float(rr[1])); }
;   if (__builtin_expect(__all(pmax - m_reg <= ATHR / ASCALE), 1)) { mn = m_reg; alpha = 1.f; }
;   else { mn = fmaxf(m_reg, pmax); alpha = __builtin_amdgcn_exp2f((m_reg - mn) * C); m_reg = mn; }
;   float mnC = -mn * C;
; #pragma unroll
;   for (int r = 0; r < 16; ++r) p0[r] = fmaf(p0[r], C, mnC);
; #pragma unroll
;   for (int r = 0; r < 16; ++r) p1[r] = fmaf(p1[r], C, mnC);
; #pragma unroll
;   for (int r = 0; r < 16; ++r) p0[r] = __builtin_amdgcn_exp2f(p0[r]);
; }
; DEVI void attn_item(const u16* __restrict__ Qb, const u16* __restrict__ KNh, const u16* __restrict__ VTh, int Lpad, const u16* __restrict__ KRb,
;                     const u16* __restrict__ SZb, u16* __restrict__ AOb, int NT, char* lds, const int wid_s_) {
;     ...
;   float m_reg = -1e30f, l_reg = 0; f32x16 o[4] = {}; bf16x8 qr[8];
;   const u16* Qw = Qb + (size_t)(wid * 32 + r32) * LDQ + hi * 8;
; #pragma unroll
;   for (int d0 = 0; d0 < 8; ++d0) qr[d0] = __builtin_nontemporal_load(reinterpret_cast<const bf16x8*>(Qw + d0 * 16));
; #pragma unroll
;   for (int d0 = 0; d0 < 4; ++d0) *reinterpret_cast<bf16x8*>(Qrs + RSWZ(r32, (d0 * 16 + hi * 8) * 2)) = *reinterpret_cast<const bf16x8*>(Qw + 128 + d0 * 16);
;   const int sr = tid >> 4, sc = (tid & 15) * 8;
;   const int vd = tid >> 3, vc = tid & 7;
;   const int rr_ = tid >> 3, rc_ = (tid & 7) * 8;
;   bf16x8 vs0, vs1, ks0, ks1, rs0;
;   const unsigned vo_k = (unsigned)((sr * LDK + sc) * 2), vo_r = (unsigned)((rr_ * 64 + rc_) * 2), vo_v = (unsigned)((vd * Lpad + vc * 8) * 2);
;   const size_t vhalf = (size_t)64 * Lpad * 2;
;     ...
;   f32x16 pA0, pA1, pB0, pB1; float mnA, mnB, alA, alB; bf16x8 pa0, pa1, pa2, pa3;
;   SLOAD(0); SWAIT(); SWRITE(0); __syncthreads();
;   qkt(pA0, pA1, K_lds, R_lds, qr, Qrs, r32, hi); partialSM(pA0, pA1, m_reg, mnA, alA);
	ds_write_b128 v185, v[52:55] offset:24576
	v_mov_b64_e32 v[30:31], s[26:27]
	v_mov_b64_e32 v[28:29], s[24:25]
	s_nop 3
	v_max_f32_e32 v72, v1, v1
	v_max_f32_e32 v73, v0, v0
	v_mfma_f32_32x32x16_bf16 v[32:47], v[76:79], v[80:83], v[32:47]
	v_max_f32_e32 v72, v73, v72
	v_max3_f32 v72, v72, v2, v3
	v_max3_f32 v72, v72, v4, v5
	v_max3_f32 v72, v72, v6, v7
	v_max3_f32 v72, v72, v8, v9
	v_max3_f32 v72, v72, v10, v11
	v_max3_f32 v72, v72, v12, v13
	v_max3_f32 v72, v72, v14, v15
	s_nop 3
	v_max3_f32 v72, v72, v32, v33
	v_max3_f32 v72, v72, v34, v35
	v_max3_f32 v72, v72, v36, v37
	v_max3_f32 v72, v72, v38, v39
	v_max3_f32 v72, v72, v40, v41
	v_max3_f32 v72, v72, v42, v43
	v_max3_f32 v72, v72, v44, v45
	v_max3_f32 v72, v72, v46, v47
	v_mov_b32_e32 v73, v72
	s_nop 1
	v_permlane32_swap_b32_e32 v72, v73
	v_max_f32_e32 v73, v73, v73
	v_max_f32_e32 v72, v72, v72
	v_max_f32_e32 v72, v72, v73
	v_add_f32_e32 v73, 0x7149f2ca, v72
	v_cmp_ge_f32_e32 vcc, s91, v73
	s_cmp_eq_u64 vcc, exec
	v_max_f32_e32 v53, 0xf149f2ca, v72
	s_cselect_b64 vcc, -1, 0
	v_cndmask_b32_e32 v222, v53, v208, vcc
	v_mul_f32_e32 v52, 0xbdd53b94, v222
	v_fmamk_f32 v0, v0, 0x3dd53b94, v52
	v_exp_f32_e32 v231, v0
	v_fmamk_f32 v0, v1, 0x3dd53b94, v52
	v_exp_f32_e32 v235, v0
	v_fmamk_f32 v0, v2, 0x3dd53b94, v52
	v_exp_f32_e32 v230, v0
	v_fmamk_f32 v0, v3, 0x3dd53b94, v52
	v_exp_f32_e32 v232, v0
	v_fmamk_f32 v0, v4, 0x3dd53b94, v52
	v_exp_f32_e32 v233, v0
	v_fmamk_f32 v0, v5, 0x3dd53b94, v52
	v_exp_f32_e32 v236, v0
	v_fmamk_f32 v0, v6, 0x3dd53b94, v52
	v_exp_f32_e32 v234, v0
	v_fmamk_f32 v0, v7, 0x3dd53b94, v52
	v_exp_f32_e32 v237, v0
	v_fmamk_f32 v0, v8, 0x3dd53b94, v52
	v_exp_f32_e32 v156, v0
	v_fmamk_f32 v0, v9, 0x3dd53b94, v52
	v_exp_f32_e32 v157, v0
	v_fmamk_f32 v0, v10, 0x3dd53b94, v52
	v_exp_f32_e32 v158, v0
	v_fmamk_f32 v0, v11, 0x3dd53b94, v52
	v_exp_f32_e32 v159, v0
	v_fmamk_f32 v0, v12, 0x3dd53b94, v52
	v_exp_f32_e32 v228, v0
	v_fmamk_f32 v0, v13, 0x3dd53b94, v52
	v_exp_f32_e32 v229, v0
	v_fmamk_f32 v0, v14, 0x3dd53b94, v52
	v_sub_f32_e32 v1, 0xf149f2ca, v53
	v_mul_f32_e32 v1, 0x3dd53b94, v1
	v_exp_f32_e32 v154, v0
	v_mov_b32_e32 v0, s46
	v_mov_b64_e32 v[26:27], s[22:23]
	v_mov_b64_e32 v[24:25], s[20:21]
	v_mov_b64_e32 v[22:23], s[18:19]
	v_mov_b64_e32 v[20:21], s[16:17]
	v_mov_b64_e32 v[18:19], s[14:15]
	v_mov_b64_e32 v[16:17], s[12:13]
	v_exp_f32_e32 v1, v1
	v_mad_u64_u32 v[162:163], s[14:15], s64, v0, v[50:51]
	v_add_u32_e32 v162, s75, v162
	v_pk_fma_f32 v[144:145], v[46:47], s[80:81], v[52:53] op_sel_hi:[1,0,0]
	v_pk_fma_f32 v[140:141], v[44:45], s[80:81], v[52:53] op_sel_hi:[1,0,0]
	v_pk_fma_f32 v[146:147], v[42:43], s[80:81], v[52:53] op_sel_hi:[1,0,0]
	v_pk_fma_f32 v[142:143], v[40:41], s[80:81], v[52:53] op_sel_hi:[1,0,0]
	v_pk_fma_f32 v[148:149], v[38:39], s[80:81], v[52:53] op_sel_hi:[1,0,0]
	v_pk_fma_f32 v[150:151], v[36:37], s[80:81], v[52:53] op_sel_hi:[1,0,0]
	v_pk_fma_f32 v[152:153], v[34:35], s[80:81], v[52:53] op_sel_hi:[1,0,0]
	v_pk_fma_f32 v[80:81], v[32:33], s[80:81], v[52:53] op_sel_hi:[1,0,0]
	v_fmac_f32_e32 v52, 0x3dd53b94, v15
	s_lshl_b64 s[14:15], s[46:47], 1
	v_exp_f32_e32 v155, v52
	s_or_b32 s13, s14, 0x80
	v_mov_b32_e32 v0, s13
	v_cndmask_b32_e64 v220, v1, 1.0, vcc
	v_mad_u64_u32 v[164:165], s[16:17], s28, v0, v[50:51]
	s_mul_i32 s13, s28, s15
	s_or_b32 s8, s8, s1
	v_mov_b64_e32 v[62:63], v[30:31]
	v_mov_b64_e32 v[46:47], v[30:31]
	v_mov_b64_e32 v[0:1], v[16:17]
	v_add_u32_e32 v165, s13, v165
	v_add_u32_e32 v164, s75, v164
	v_lshl_add_u64 v[168:169], s[8:9], 0, v[204:205]
	v_add_u32_e32 v168, 0x22681000, v168
	v_mov_b64_e32 v[60:61], v[28:29]
	v_mov_b64_e32 v[58:59], v[26:27]
	v_mov_b64_e32 v[56:57], v[24:25]
	v_mov_b64_e32 v[54:55], v[22:23]
	v_mov_b64_e32 v[52:53], v[20:21]
	v_mov_b64_e32 v[50:51], v[18:19]
	v_mov_b64_e32 v[48:49], v[16:17]
	v_mov_b64_e32 v[44:45], v[28:29]
	v_mov_b64_e32 v[42:43], v[26:27]
	v_mov_b64_e32 v[40:41], v[24:25]
	v_mov_b64_e32 v[38:39], v[22:23]
	v_mov_b64_e32 v[36:37], v[20:21]
	v_mov_b64_e32 v[34:35], v[18:19]
	v_mov_b64_e32 v[32:33], v[16:17]
	v_mov_b64_e32 v[2:3], v[18:19]
	v_mov_b64_e32 v[4:5], v[20:21]
	v_mov_b64_e32 v[6:7], v[22:23]
	v_mov_b64_e32 v[8:9], v[24:25]
	v_mov_b64_e32 v[10:11], v[26:27]
	v_mov_b64_e32 v[12:13], v[28:29]
	v_mov_b64_e32 v[14:15], v[30:31]
	s_waitcnt lgkmcnt(0)
	s_barrier
; #define SBAR() __builtin_amdgcn_sched_barrier(0)
; DEVI void finishSM(f32x16& p0, f32x16& p1, float alpha, float& l_reg, bf16x8& pa0, bf16x8& pa1, bf16x8& pa2, bf16x8& pa3) {
; #pragma unroll
;   for (int r = 0; r < 16; ++r) p1[r] = __builtin_amdgcn_exp2f(p1[r]);
;   float ps = 0;
; #pragma unroll
;   for (int r = 0; r < 16; ++r) ps += p0[r];
; #pragma unroll
;   for (int r = 0; r < 16; ++r) ps += p1[r];
;   { auto rr = __builtin_amdgcn_permlane32_swap(__float_as_uint(ps), __float_as_uint(ps), false, false);
;     ps = __uint_as_float(rr[0]) + __uint_as_float(rr[1]); }
;   l_reg = l_reg * alpha + ps;
;     ...
;   PK4(p0, 0, pa0); PK4(p0, 8, pa1); PK4(p1, 0, pa2); PK4(p1, 8, pa3);
;     ...
; }
; DEVI void mask_tile(f32x16& p0, f32x16& p1, bool nv16) {
; #pragma unroll
;   for (int r = 0; r < 16; ++r) { if (!(nv16 && r < 8)) p0[r] = -1e30f; p1[r] = -1e30f; }
; }
; DEVI void qkt(f32x16& p0, f32x16& p1, const char* Ks, const char* Rs, const bf16x8* qr, const char* Qrs, int r32, int hi) {
;   p0 = f32x16{}; p1 = f32x16{};
; #pragma unroll
;   for (int d0 = 0; d0 < 8; ++d0) { int cb = (d0 * 16 + hi * 8) * 2;
;     bf16x8 b0 = *reinterpret_cast<const bf16x8*>(Ks + KSWZ(r32, cb));
;     bf16x8 b1 = *reinterpret_cast<const bf16x8*>(Ks + KSWZ(32 + r32, cb));
;     p0 = __builtin_amdgcn_mfma_f32_32x32x16_bf16(b0, qr[d0], p0, 0, 0, 0);
;     p1 = __builtin_amdgcn_mfma_f32_32x32x16_bf16(b1, qr[d0], p1, 0, 0, 0); }
; #pragma unroll
;   for (int d0 = 0; d0 < 4; ++d0) { int cb = (d0 * 16 + hi * 8) * 2;
;     bf16x8 b0 = *reinterpret_cast<const bf16x8*>(Rs + RSWZ(r32, cb));
;     bf16x8 b1 = *reinterpret_cast<const bf16x8*>(Rs + RSWZ(32 + r32, cb));
;     bf16x8 qf = *reinterpret_cast<const bf16x8*>(Qrs + RSWZ(r32, cb));
;     p0 = __builtin_amdgcn_mfma_f32_32x32x16_bf16(b0, qf, p0, 0, 0, 0);
;     p1 = __builtin_amdgcn_mfma_f32_32x32x16_bf16(b1, qf, p1, 0, 0, 0); }
; }
; DEVI void attn_item(const u16* __restrict__ Qb, const u16* __restrict__ KNh, const u16* __restrict__ VTh, int Lpad, const u16* __restrict__ KRb,
;                     const u16* __restrict__ SZb, u16* __restrict__ AOb, int NT, char* lds, const int wid_s_) {
;     ...
;   for (int j = 1; j + 1 < NT; j += 2) {
;     SLOAD_KR((j + 1) * 64);
;     SBAR(); qkt(pB0, pB1, K_lds + SHM_K, R_lds + SHM_R, qr, Qrs, r32, hi);
;     finishSM(pA0, pA1, alA, l_reg, pa0, pa1, pa2, pa3); SGB_QK(); SBAR();
.LBB0_981:
	global_load_dwordx4 v[128:131], v168, s[36:37] offset:3072
	v_add_u32_e32 v64, 0x20000, v168
	global_load_dwordx4 v[132:135], v64, s[36:37] offset:3072
	global_load_dwordx4 v[136:139], v166, s[36:37] offset:3072
	ds_read_b128 v[64:67], v187 offset:49152
	v_or_b32_e32 v204, 0x12000, v177
	v_or_b32_e32 v224, 0x13000, v177
	v_add_u32_e32 v225, v183, v177
	v_exp_f32_e32 v242, v80
	s_waitcnt lgkmcnt(0)
	v_mfma_f32_32x32x16_bf16 v[64:79], v[64:67], v[96:99], 0
	ds_read_b128 v[82:85], v187 offset:57344
	v_or_b32_e32 v243, 0x12000, v161
	v_or_b32_e32 v244, 0x13000, v161
	v_add_u32_e32 v223, v183, v161
	v_exp_f32_e32 v245, v81
	s_waitcnt lgkmcnt(0)
	v_mfma_f32_32x32x16_bf16 v[80:95], v[82:85], v[96:99], 0
	ds_read_b128 v[238:241], v188 offset:49152
	v_or_b32_e32 v246, 0x12000, v180
	v_or_b32_e32 v247, 0x13000, v180
	v_add_u32_e32 v227, v183, v180
	v_exp_f32_e32 v248, v152
	s_waitcnt lgkmcnt(0)
	v_mfma_f32_32x32x16_bf16 v[64:79], v[238:241], v[100:103], v[64:79]
	ds_read_b128 v[238:241], v188 offset:57344
	v_or_b32_e32 v249, 0x12000, v179
	v_or_b32_e32 v250, 0x13000, v179
	v_add_u32_e32 v226, v183, v179
	v_exp_f32_e32 v251, v153
	s_waitcnt lgkmcnt(0)
	v_mfma_f32_32x32x16_bf16 v[80:95], v[238:241], v[100:103], v[80:95]
	ds_read_b128 v[238:241], v189 offset:49152
	v_add_f32_e32 v152, 0, v231
	v_add_f32_e32 v152, v235, v152
	v_add_f32_e32 v152, v230, v152
	v_exp_f32_e32 v252, v150
	s_waitcnt lgkmcnt(0)
	v_mfma_f32_32x32x16_bf16 v[64:79], v[238:241], v[104:107], v[64:79]
	ds_read_b128 v[238:241], v189 offset:57344
	v_add_f32_e32 v150, v232, v152
	v_add_f32_e32 v150, v233, v150
	v_add_f32_e32 v221, v236, v150
	v_exp_f32_e32 v253, v151
	s_waitcnt lgkmcnt(0)
	v_mfma_f32_32x32x16_bf16 v[80:95], v[238:241], v[104:107], v[80:95]
	ds_read_b128 v[150:153], v190 offset:49152
	v_add_f32_e32 v221, v234, v221
	v_add_f32_e32 v221, v237, v221
	v_add_f32_e32 v221, v156, v221
	v_exp_f32_e32 v209, v148
	s_waitcnt lgkmcnt(0)
	v_mfma_f32_32x32x16_bf16 v[64:79], v[150:153], v[108:111], v[64:79]
	ds_read_b128 v[150:153], v190 offset:57344
	v_add_f32_e32 v148, v157, v221
	v_add_f32_e32 v148, v158, v148
	v_add_f32_e32 v221, v159, v148
	v_exp_f32_e32 v210, v149
	s_waitcnt lgkmcnt(0)
	v_mfma_f32_32x32x16_bf16 v[80:95], v[150:153], v[108:111], v[80:95]
	ds_read_b128 v[148:151], v191 offset:49152
	v_add_f32_e32 v152, v228, v221
	v_add_f32_e32 v152, v229, v152
	v_add_f32_e32 v152, v154, v152
	v_exp_f32_e32 v211, v142
	s_waitcnt lgkmcnt(0)
	v_mfma_f32_32x32x16_bf16 v[64:79], v[148:151], v[112:115], v[64:79]
	ds_read_b128 v[148:151], v191 offset:57344
	v_add_f32_e32 v142, v155, v152
	v_add_f32_e32 v142, v242, v142
	v_add_f32_e32 v142, v245, v142
	v_exp_f32_e32 v212, v143
	s_waitcnt lgkmcnt(0)
	v_mfma_f32_32x32x16_bf16 v[80:95], v[148:151], v[112:115], v[80:95]
	ds_read_b128 v[148:151], v192 offset:49152
	v_add_f32_e32 v142, v248, v142
	v_add_f32_e32 v142, v251, v142
	v_add_f32_e32 v142, v252, v142
	v_exp_f32_e32 v214, v146
	s_waitcnt lgkmcnt(0)
	v_mfma_f32_32x32x16_bf16 v[64:79], v[148:151], v[116:119], v[64:79]
	ds_read_b128 v[148:151], v192 offset:57344
	v_add_f32_e32 v142, v253, v142
	v_add_f32_e32 v142, v209, v142
	v_add_f32_e32 v142, v210, v142
	v_exp_f32_e32 v215, v147
	s_waitcnt lgkmcnt(0)
	v_mfma_f32_32x32x16_bf16 v[80:95], v[148:151], v[116:119], v[80:95]
	ds_read_b128 v[146:149], v193 offset:49152
	v_add_f32_e32 v142, v211, v142
	v_add_f32_e32 v142, v212, v142
	v_add_f32_e32 v142, v214, v142
	v_exp_f32_e32 v216, v140
	s_waitcnt lgkmcnt(0)
	v_mfma_f32_32x32x16_bf16 v[64:79], v[146:149], v[120:123], v[64:79]
	ds_read_b128 v[146:149], v193 offset:57344
	v_add_f32_e32 v142, v215, v142
	v_cvt_pk_bf16_f32 v140, v231, v235
	v_add_f32_e32 v142, v216, v142
	v_exp_f32_e32 v217, v141
	s_waitcnt lgkmcnt(0)
	v_mfma_f32_32x32x16_bf16 v[80:95], v[146:149], v[120:123], v[80:95]
	ds_read_b128 v[146:149], v194 offset:49152
	v_add_f32_e32 v143, v217, v142
	v_cvt_pk_bf16_f32 v141, v230, v232
	v_cvt_pk_bf16_f32 v142, v233, v236
	v_exp_f32_e32 v218, v144
	s_waitcnt lgkmcnt(0)
	v_mfma_f32_32x32x16_bf16 v[64:79], v[146:149], v[124:127], v[64:79]
	ds_read_b128 v[146:149], v194 offset:57344
	v_add_f32_e32 v144, v218, v143
	v_cvt_pk_bf16_f32 v143, v234, v237
	v_permlane32_swap_b32_e32 v140, v142
	v_exp_f32_e32 v219, v145
	s_waitcnt lgkmcnt(0)
	v_mfma_f32_32x32x16_bf16 v[80:95], v[146:149], v[124:127], v[80:95]
	ds_read_b128 v[148:151], v204
	v_add_f32_e32 v204, v219, v144
	v_permlane32_swap_b32_e32 v141, v143
	v_mov_b32_e32 v221, v204
	ds_read_b128 v[230:233], v224
	v_cvt_pk_bf16_f32 v144, v156, v157
	v_cvt_pk_bf16_f32 v145, v158, v159
	ds_read_b128 v[156:159], v225
	v_cvt_pk_bf16_f32 v146, v228, v229
	ds_read_b128 v[234:237], v223
	s_waitcnt lgkmcnt(1)
	v_mfma_f32_32x32x16_bf16 v[80:95], v[230:233], v[156:159], v[80:95]
	ds_read_b128 v[228:231], v244
	s_waitcnt lgkmcnt(0)
	v_mfma_f32_32x32x16_bf16 v[80:95], v[228:231], v[234:237], v[80:95]
	ds_read_b128 v[228:231], v247
	ds_read_b128 v[238:241], v227
	s_waitcnt lgkmcnt(0)
	v_mfma_f32_32x32x16_bf16 v[80:95], v[228:231], v[238:241], v[80:95]
	v_permlane32_swap_b32_e32 v204, v221
	v_cvt_pk_bf16_f32 v147, v154, v155
	v_permlane32_swap_b32_e32 v144, v146
	ds_read_b128 v[228:231], v250
	v_mfma_f32_32x32x16_bf16 v[64:79], v[148:151], v[156:159], v[64:79]
	v_permlane32_swap_b32_e32 v145, v147
	ds_read_b128 v[148:151], v243
	v_cvt_pk_bf16_f32 v155, v218, v219
	ds_read_b128 v[156:159], v226
	s_waitcnt lgkmcnt(1)
	v_mfma_f32_32x32x16_bf16 v[64:79], v[148:151], v[234:237], v[64:79]
	ds_read_b128 v[148:151], v246
	v_cvt_pk_bf16_f32 v154, v216, v217
	s_waitcnt lgkmcnt(0)
	v_mfma_f32_32x32x16_bf16 v[64:79], v[148:151], v[238:241], v[64:79]
	ds_read_b128 v[150:153], v249
	s_waitcnt lgkmcnt(0)
; #define SBAR() __builtin_amdgcn_sched_barrier(0)
; #define SGB_QK() _Pragma("unroll") for (int g_ = 0; g_ < 24; ++g_) { __builtin_amdgcn_sched_group_barrier(0x008, 1, 0); __builtin_amdgcn_sched_group_barrier(0x100, 1, 0); \
;     __builtin_amdgcn_sched_group_barrier(0x002, 3, 0); __builtin_amdgcn_sched_group_barrier(0x400, 1, 0); }
; #define SLOAD(k0) do { SLOAD_KR(k0); SLOAD_V(k0); } while (0)
; #define SWRITE(b) do { SWRITE_KR(b); SWRITE_V(b); } while (0)
; DEVI void pv_d0(f32x16* o, const char* Vs, int r32, int hi, bf16x8 pa0, bf16x8 pa1, bf16x8 pa2, bf16x8 pa3) {
; #pragma unroll
;   for (int d0 = 0; d0 < 4; ++d0) {
;     const bf16x8 f0 = *reinterpret_cast<const bf16x8*>(Vs + RSWZ(d0 * 32 + r32, (0 * 16 + hi * 8) * 2));
;     const bf16x8 f1 = *reinterpret_cast<const bf16x8*>(Vs + RSWZ(d0 * 32 + r32, (1 * 16 + hi * 8) * 2));
;     const bf16x8 f2 = *reinterpret_cast<const bf16x8*>(Vs + RSWZ(d0 * 32 + r32, (2 * 16 + hi * 8) * 2));
;     const bf16x8 f3 = *reinterpret_cast<const bf16x8*>(Vs + RSWZ(d0 * 32 + r32, (3 * 16 + hi * 8) * 2));
;     o[d0] = __builtin_amdgcn_mfma_f32_32x32x16_bf16(pa0, f0, o[d0], 0, 0, 0);
;     o[d0] = __builtin_amdgcn_mfma_f32_32x32x16_bf16(pa1, f1, o[d0], 0, 0, 0);
;     o[d0] = __builtin_amdgcn_mfma_f32_32x32x16_bf16(pa2, f2, o[d0], 0, 0, 0);
;     o[d0] = __builtin_amdgcn_mfma_f32_32x32x16_bf16(pa3, f3, o[d0], 0, 0, 0);
;   }
; }
; DEVI void attn_item(const u16* __restrict__ Qb, const u16* __restrict__ KNh, const u16* __restrict__ VTh, int Lpad, const u16* __restrict__ KRb,
;                     const u16* __restrict__ SZb, u16* __restrict__ AOb, int NT, char* lds, const int wid_s_) {
;     ...
;   f32x16 pA0, pA1, pB0, pB1; float mnA, mnB, alA, alB; bf16x8 pa0, pa1, pa2, pa3;
;   SLOAD(0); SWAIT(); SWRITE(0); __syncthreads();
;   qkt(pA0, pA1, K_lds, R_lds, qr, Qrs, r32, hi); partialSM(pA0, pA1, m_reg, mnA, alA);
;   SLOAD(64);
;   SWAIT(); SWRITE(1); __syncthreads();
;   for (int j = 1; j + 1 < NT; j += 2) {
;     SLOAD_KR((j + 1) * 64);
;     SBAR(); qkt(pB0, pB1, K_lds + SHM_K, R_lds + SHM_R, qr, Qrs, r32, hi);
;     finishSM(pA0, pA1, alA, l_reg, pa0, pa1, pa2, pa3); SGB_QK(); SBAR();
;     SLOAD_V((j + 1) * 64); SBAR();
;     pv_d0(o, V_lds, r32, hi, pa0, pa1, pa2, pa3); partialSM(pB0, pB1, m_reg, mnB, alB);
;     SWRITE_KR(0);
;     __syncthreads(); SWAIT(); SWRITE_V(0);
;     RESC(alB); __syncthreads();
	v_mfma_f32_32x32x16_bf16 v[64:79], v[150:153], v[156:159], v[64:79]
	v_cvt_pk_bf16_f32 v153, v214, v215
	v_cvt_pk_bf16_f32 v152, v211, v212
	v_cvt_pk_bf16_f32 v151, v209, v210
	v_cvt_pk_bf16_f32 v149, v248, v251
	s_nop 1
	v_permlane32_swap_b32_e32 v149, v151
	v_cvt_pk_bf16_f32 v148, v242, v245
	v_mfma_f32_32x32x16_bf16 v[80:95], v[228:231], v[156:159], v[80:95]
	v_cvt_pk_bf16_f32 v150, v252, v253
	s_nop 1
	v_permlane32_swap_b32_e32 v148, v150
	v_permlane32_swap_b32_e32 v152, v154
	v_permlane32_swap_b32_e32 v153, v155
	global_load_dwordx4 v[228:231], v162, s[36:37] offset:3328
	global_load_dwordx4 v[232:235], v164, s[36:37] offset:3328
	ds_read_b128 v[236:239], v177
	ds_read_b128 v[240:243], v161
	ds_read_b128 v[244:247], v180
	ds_read_b128 v[248:251], v179
	s_waitcnt lgkmcnt(3)
	v_mfma_f32_32x32x16_bf16 v[16:31], v[140:143], v[236:239], v[16:31]
	ds_read_b128 v[236:239], v177 offset:4096
	s_waitcnt lgkmcnt(3)
	v_mfma_f32_32x32x16_bf16 v[16:31], v[144:147], v[240:243], v[16:31]
	ds_read_b128 v[240:243], v161 offset:4096
	s_waitcnt lgkmcnt(1)
	v_mfma_f32_32x32x16_bf16 v[48:63], v[140:143], v[236:239], v[48:63]
	ds_read_b128 v[236:239], v177 offset:8192
	v_mfma_f32_32x32x16_bf16 v[16:31], v[148:151], v[244:247], v[16:31]
	ds_read_b128 v[244:247], v180 offset:4096
	s_waitcnt lgkmcnt(2)
	v_mfma_f32_32x32x16_bf16 v[48:63], v[144:147], v[240:243], v[48:63]
	ds_read_b128 v[240:243], v161 offset:8192
	s_waitcnt lgkmcnt(2)
	v_mfma_f32_32x32x16_bf16 v[32:47], v[140:143], v[236:239], v[32:47]
	ds_read_b128 v[236:239], v177 offset:12288
	v_mfma_f32_32x32x16_bf16 v[16:31], v[152:155], v[248:251], v[16:31]
	ds_read_b128 v[248:251], v179 offset:4096
	s_waitcnt lgkmcnt(3)
	v_mfma_f32_32x32x16_bf16 v[48:63], v[148:151], v[244:247], v[48:63]
	ds_read_b128 v[244:247], v180 offset:8192
	s_waitcnt lgkmcnt(3)
	v_mfma_f32_32x32x16_bf16 v[32:47], v[144:147], v[240:243], v[32:47]
	ds_read_b128 v[240:243], v161 offset:12288
	s_waitcnt lgkmcnt(3)
	v_mfma_f32_32x32x16_bf16 v[0:15], v[140:143], v[236:239], v[0:15]
	v_max_f32_e32 v140, v65, v65
	v_max_f32_e32 v141, v64, v64
	v_max_f32_e32 v140, v141, v140
	v_max3_f32 v140, v140, v66, v67
	v_max3_f32 v140, v140, v68, v69
	v_max3_f32 v140, v140, v70, v71
	v_max3_f32 v140, v140, v72, v73
	v_max3_f32 v140, v140, v74, v75
	v_max3_f32 v140, v140, v76, v77
	s_waitcnt lgkmcnt(2)
	v_mfma_f32_32x32x16_bf16 v[48:63], v[152:155], v[248:251], v[48:63]
	ds_read_b128 v[248:251], v179 offset:8192
	v_max3_f32 v140, v140, v78, v79
	v_max3_f32 v140, v140, v80, v81
	v_max3_f32 v140, v140, v82, v83
	v_max3_f32 v140, v140, v84, v85
	v_max3_f32 v140, v140, v86, v87
	v_max3_f32 v140, v140, v88, v89
	s_waitcnt lgkmcnt(2)
	v_mfma_f32_32x32x16_bf16 v[32:47], v[148:151], v[244:247], v[32:47]
	ds_read_b128 v[244:247], v180 offset:12288
	v_max3_f32 v140, v140, v90, v91
	v_max3_f32 v140, v140, v92, v93
	v_max3_f32 v140, v140, v94, v95
	v_mov_b32_e32 v141, v140
	s_nop 1
	v_permlane32_swap_b32_e32 v140, v141
	s_waitcnt lgkmcnt(2)
	v_mfma_f32_32x32x16_bf16 v[0:15], v[144:147], v[240:243], v[0:15]
	v_max_f32_e32 v141, v141, v141
	v_max_f32_e32 v140, v140, v140
	v_max_f32_e32 v140, v140, v141
	v_sub_f32_e32 v141, v140, v222
	v_cmp_ge_f32_e32 vcc, s91, v141
	v_max_f32_e32 v141, v222, v222
	v_max_f32_e32 v140, v141, v140
	s_waitcnt lgkmcnt(1)
	v_mfma_f32_32x32x16_bf16 v[32:47], v[152:155], v[248:251], v[32:47]
	ds_read_b128 v[248:251], v179 offset:12288
	v_sub_f32_e32 v141, v222, v140
	v_mul_f32_e32 v141, 0x3dd53b94, v141
	v_exp_f32_e32 v141, v141
	s_cmp_eq_u64 vcc, exec
	s_cselect_b64 s[8:9], -1, 0
	s_waitcnt vmcnt(2)
	ds_write_b128 v184, v[128:131] offset:32768
	s_waitcnt lgkmcnt(2)
	v_mfma_f32_32x32x16_bf16 v[0:15], v[148:151], v[244:247], v[0:15]
	ds_write_b128 v184, v[132:135] offset:40960
	ds_write_b128 v186, v[136:139]
	s_waitcnt lgkmcnt(0)
	s_barrier
	s_waitcnt vmcnt(0)
	v_cndmask_b32_e64 v224, v141, 1.0, s[8:9]
	v_mfma_f32_32x32x16_bf16 v[0:15], v[152:155], v[248:251], v[0:15]
	v_cmp_gt_f32_e32 vcc, 1.0, v224
	ds_write_b128 v185, v[228:231]
	ds_write_b128 v185, v[232:235] offset:8192
	s_cbranch_vccz .LBB0_985
	s_and_saveexec_b64 s[14:15], s[6:7]
	ds_write_b32 v181, v224 offset:128
	s_or_b64 exec, exec, s[14:15]
	s_waitcnt lgkmcnt(0)
	v_add_u32_e32 v141, v178, v160
	ds_read_b128 v[128:131], v141 offset:224
	ds_read_b128 v[132:135], v141 offset:192
	ds_read_b128 v[136:139], v141 offset:160
	ds_read_b128 v[142:145], v141 offset:128
	s_waitcnt lgkmcnt(3)
	v_pk_mul_f32 v[28:29], v[28:29], v[128:129]
	s_waitcnt lgkmcnt(2)
	v_pk_mul_f32 v[24:25], v[24:25], v[132:133]
	s_waitcnt lgkmcnt(1)
	v_pk_mul_f32 v[20:21], v[20:21], v[136:137]
	v_pk_mul_f32 v[30:31], v[30:31], v[130:131]
	v_pk_mul_f32 v[26:27], v[26:27], v[134:135]
	v_pk_mul_f32 v[22:23], v[22:23], v[138:139]
	s_waitcnt lgkmcnt(0)
	v_pk_mul_f32 v[18:19], v[18:19], v[144:145]
	v_pk_mul_f32 v[16:17], v[16:17], v[142:143]
	v_pk_mul_f32 v[60:61], v[60:61], v[128:129]
	v_pk_mul_f32 v[56:57], v[56:57], v[132:133]
	v_pk_mul_f32 v[52:53], v[52:53], v[136:137]
	v_pk_mul_f32 v[62:63], v[62:63], v[130:131]
	v_pk_mul_f32 v[58:59], v[58:59], v[134:135]
	v_pk_mul_f32 v[54:55], v[54:55], v[138:139]
	v_pk_mul_f32 v[50:51], v[50:51], v[144:145]
	v_pk_mul_f32 v[48:49], v[48:49], v[142:143]
	v_pk_mul_f32 v[44:45], v[44:45], v[128:129]
	v_pk_mul_f32 v[40:41], v[40:41], v[132:133]
	v_pk_mul_f32 v[36:37], v[36:37], v[136:137]
	v_pk_mul_f32 v[46:47], v[46:47], v[130:131]
	v_pk_mul_f32 v[42:43], v[42:43], v[134:135]
	v_pk_mul_f32 v[38:39], v[38:39], v[138:139]
	v_pk_mul_f32 v[34:35], v[34:35], v[144:145]
	v_pk_mul_f32 v[32:33], v[32:33], v[142:143]
	v_pk_mul_f32 v[12:13], v[12:13], v[128:129]
	v_pk_mul_f32 v[8:9], v[8:9], v[132:133]
	v_pk_mul_f32 v[4:5], v[4:5], v[136:137]
	v_pk_mul_f32 v[14:15], v[14:15], v[130:131]
	v_pk_mul_f32 v[10:11], v[10:11], v[134:135]
	v_pk_mul_f32 v[6:7], v[6:7], v[138:139]
	v_pk_mul_f32 v[2:3], v[2:3], v[144:145]
	v_pk_mul_f32 v[0:1], v[0:1], v[142:143]
; #define SBAR() __builtin_amdgcn_sched_barrier(0)
; #define SGB_QK() _Pragma("unroll") for (int g_ = 0; g_ < 24; ++g_) { __builtin_amdgcn_sched_group_barrier(0x008, 1, 0); __builtin_amdgcn_sched_group_barrier(0x100, 1, 0); \
;     __builtin_amdgcn_sched_group_barrier(0x002, 3, 0); __builtin_amdgcn_sched_group_barrier(0x400, 1, 0); }
; #define SLOAD_KR(k0) do { const char* kb_ = (const char*)KNh + (size_t)(k0) * (LDK * 2); const char* kb2_ = kb_ + 32 * LDK * 2; const char* rb_ = (const char*)KRb + (size_t)(k0) * 128; \
;     ks0 = *reinterpret_cast<const bf16x8*>(kb_ + vo_k); ks1 = *reinterpret_cast<const bf16x8*>(kb2_ + vo_k);               \
;     rs0 = *reinterpret_cast<const bf16x8*>(rb_ + vo_r); } while (0)
; DEVI void partialSM(f32x16& p0, f32x16& p1, float& m_reg, float& mn, float& alpha) {
;     ...
;   else { mn = fmaxf(m_reg, pmax); alpha = __builtin_amdgcn_exp2f((m_reg - mn) * C); m_reg = mn; }
;   float mnC = -mn * C;
; #pragma unroll
;   for (int r = 0; r < 16; ++r) p0[r] = fmaf(p0[r], C, mnC);
; #pragma unroll
;   for (int r = 0; r < 16; ++r) p1[r] = fmaf(p1[r], C, mnC);
; #pragma unroll
;   for (int r = 0; r < 16; ++r) p0[r] = __builtin_amdgcn_exp2f(p0[r]);
; }
; DEVI void finishSM(f32x16& p0, f32x16& p1, float alpha, float& l_reg, bf16x8& pa0, bf16x8& pa1, bf16x8& pa2, bf16x8& pa3) {
; #pragma unroll
;   for (int r = 0; r < 16; ++r) p1[r] = __builtin_amdgcn_exp2f(p1[r]);
;   float ps = 0;
; #pragma unroll
;   for (int r = 0; r < 16; ++r) ps += p0[r];
; #pragma unroll
;   for (int r = 0; r < 16; ++r) ps += p1[r];
;   { auto rr = __builtin_amdgcn_permlane32_swap(__float_as_uint(ps), __float_as_uint(ps), false, false);
;     ps = __uint_as_float(rr[0]) + __uint_as_float(rr[1]); }
;   l_reg = l_reg * alpha + ps;
; DEVI void attn_item(const u16* __restrict__ Qb, const u16* __restrict__ KNh, const u16* __restrict__ VTh, int Lpad, const u16* __restrict__ KRb,
;                     const u16* __restrict__ SZb, u16* __restrict__ AOb, int NT, char* lds, const int wid_s_) {
;     ...
;     SLOAD_KR((j + 2) * 64);
;     SBAR(); qkt(pA0, pA1, K_lds, R_lds, qr, Qrs, r32, hi);
;     if (j + 1 == NT - 2) mask_tile(pA0, pA1, true);
;     finishSM(pB0, pB1, alB, l_reg, pa0, pa1, pa2, pa3); SGB_QK(); SBAR();
.LBB0_985:
	v_cndmask_b32_e64 v222, v140, v222, s[8:9]
	v_mul_f32_e32 v152, 0xbdd53b94, v222
	v_fmamk_f32 v66, v66, 0x3dd53b94, v152
	v_fmamk_f32 v67, v67, 0x3dd53b94, v152
	v_exp_f32_e32 v141, v66
	v_add_u32_e32 v66, 0x40000, v168
	v_fmamk_f32 v68, v68, 0x3dd53b94, v152
	v_exp_f32_e32 v236, v67
	v_fmamk_f32 v69, v69, 0x3dd53b94, v152
	v_exp_f32_e32 v237, v68
	v_add_u32_e32 v68, 0x60000, v168
	v_fmamk_f32 v128, v64, 0x3dd53b94, v152
	v_exp_f32_e32 v238, v69
	v_exp_f32_e32 v140, v128
	s_waitcnt lgkmcnt(0)
	s_barrier
	global_load_dwordx4 v[128:131], v66, s[36:37] offset:3072
	v_add_u32_e32 v66, 0x2000, v166
	global_load_dwordx4 v[132:135], v68, s[36:37] offset:3072
	global_load_dwordx4 v[136:139], v66, s[36:37] offset:3072
	v_fmamk_f32 v74, v74, 0x3dd53b94, v152
	v_fmamk_f32 v75, v75, 0x3dd53b94, v152
	v_exp_f32_e32 v228, v74
	v_exp_f32_e32 v229, v75
	v_fmamk_f32 v65, v65, 0x3dd53b94, v152
	v_fmamk_f32 v70, v70, 0x3dd53b94, v152
	v_fmamk_f32 v71, v71, 0x3dd53b94, v152
	v_fmamk_f32 v72, v72, 0x3dd53b94, v152
	v_fmamk_f32 v73, v73, 0x3dd53b94, v152
	v_fmamk_f32 v76, v76, 0x3dd53b94, v152
	v_fmamk_f32 v77, v77, 0x3dd53b94, v152
	v_fmamk_f32 v78, v78, 0x3dd53b94, v152
	v_fmamk_f32 v79, v79, 0x3dd53b94, v152
	v_fmamk_f32 v64, v80, 0x3dd53b94, v152
	v_fmamk_f32 v80, v81, 0x3dd53b94, v152
	v_fmamk_f32 v241, v82, 0x3dd53b94, v152
	v_fmamk_f32 v145, v83, 0x3dd53b94, v152
	v_fmamk_f32 v144, v84, 0x3dd53b94, v152
	v_fmamk_f32 v143, v85, 0x3dd53b94, v152
	v_fmamk_f32 v142, v86, 0x3dd53b94, v152
	v_fmamk_f32 v239, v87, 0x3dd53b94, v152
	v_fmamk_f32 v154, v88, 0x3dd53b94, v152
	v_fmamk_f32 v150, v89, 0x3dd53b94, v152
	v_fmamk_f32 v146, v90, 0x3dd53b94, v152
	v_fmamk_f32 v147, v91, 0x3dd53b94, v152
	v_fmamk_f32 v148, v92, 0x3dd53b94, v152
	v_exp_f32_e32 v240, v65
	v_exp_f32_e32 v234, v70
	v_exp_f32_e32 v235, v71
	v_exp_f32_e32 v232, v72
	v_exp_f32_e32 v233, v73
	v_exp_f32_e32 v230, v76
	v_exp_f32_e32 v231, v77
	v_exp_f32_e32 v153, v78
	v_exp_f32_e32 v155, v79
	v_fmamk_f32 v149, v93, 0x3dd53b94, v152
	v_fmamk_f32 v151, v94, 0x3dd53b94, v152
	v_fmac_f32_e32 v152, 0x3dd53b94, v95
	ds_read_b128 v[66:69], v187 offset:32768
	v_add_f32_e32 v65, 0, v140
	v_add_f32_e32 v65, v240, v65
	v_add_f32_e32 v81, v141, v65
	v_exp_f32_e32 v209, v64
	s_cmp_eq_u32 s4, s2
	s_cselect_b64 vcc, -1, 0
	s_waitcnt lgkmcnt(0)
	v_mfma_f32_32x32x16_bf16 v[64:79], v[66:69], v[96:99], 0
	ds_read_b128 v[82:85], v187 offset:40960
	v_add_f32_e32 v81, v236, v81
	v_add_f32_e32 v81, v237, v81
	v_add_f32_e32 v210, v238, v81
	v_exp_f32_e32 v211, v80
	s_waitcnt lgkmcnt(0)
	v_mfma_f32_32x32x16_bf16 v[80:95], v[82:85], v[96:99], 0
	ds_read_b128 v[170:173], v188 offset:32768
	v_add_f32_e32 v210, v234, v210
	v_add_f32_e32 v210, v235, v210
	v_add_f32_e32 v210, v232, v210
	v_exp_f32_e32 v212, v241
	s_waitcnt lgkmcnt(0)
	v_mfma_f32_32x32x16_bf16 v[64:79], v[170:173], v[100:103], v[64:79]
	ds_read_b128 v[170:173], v188 offset:40960
	v_add_f32_e32 v210, v233, v210
	v_add_f32_e32 v210, v228, v210
	v_add_f32_e32 v210, v229, v210
	v_exp_f32_e32 v214, v145
	s_waitcnt lgkmcnt(0)
	v_mfma_f32_32x32x16_bf16 v[80:95], v[170:173], v[100:103], v[80:95]
	ds_read_b128 v[170:173], v189 offset:32768
	v_add_f32_e32 v145, v230, v210
	v_add_f32_e32 v145, v231, v145
	v_add_f32_e32 v145, v153, v145
	v_exp_f32_e32 v210, v144
	s_waitcnt lgkmcnt(0)
	v_mfma_f32_32x32x16_bf16 v[64:79], v[170:173], v[104:107], v[64:79]
	ds_read_b128 v[170:173], v189 offset:40960
	v_add_f32_e32 v144, v155, v145
	v_add_f32_e32 v144, v209, v144
	v_add_f32_e32 v144, v211, v144
	v_exp_f32_e32 v215, v143
	s_waitcnt lgkmcnt(0)
	v_mfma_f32_32x32x16_bf16 v[80:95], v[170:173], v[104:107], v[80:95]
	ds_read_b128 v[170:173], v190 offset:32768
	v_add_f32_e32 v143, v212, v144
	v_add_f32_e32 v143, v214, v143
	v_add_f32_e32 v216, v210, v143
	v_exp_f32_e32 v217, v142
	s_waitcnt lgkmcnt(0)
	v_mfma_f32_32x32x16_bf16 v[64:79], v[170:173], v[108:111], v[64:79]
	ds_read_b128 v[142:145], v190 offset:40960
	v_add_f32_e32 v170, v215, v216
	v_cvt_pk_bf16_f32 v140, v140, v240
	v_add_f32_e32 v216, v217, v170
	v_exp_f32_e32 v218, v239
	s_waitcnt lgkmcnt(0)
	v_mfma_f32_32x32x16_bf16 v[80:95], v[142:145], v[108:111], v[80:95]
	ds_read_b128 v[170:173], v191 offset:32768
	v_cvt_pk_bf16_f32 v141, v141, v236
	v_cvt_pk_bf16_f32 v142, v237, v238
	v_add_f32_e32 v143, v218, v216
	v_exp_f32_e32 v154, v154
	s_waitcnt lgkmcnt(0)
	v_mfma_f32_32x32x16_bf16 v[64:79], v[170:173], v[112:115], v[64:79]
	ds_read_b128 v[170:173], v191 offset:40960
	v_add_f32_e32 v144, v154, v143
	v_cvt_pk_bf16_f32 v143, v234, v235
	v_permlane32_swap_b32_e32 v140, v142
	v_exp_f32_e32 v216, v150
	s_waitcnt lgkmcnt(0)
	v_mfma_f32_32x32x16_bf16 v[80:95], v[170:173], v[112:115], v[80:95]
	ds_read_b128 v[170:173], v192 offset:32768
	v_add_f32_e32 v145, v216, v144
	v_permlane32_swap_b32_e32 v141, v143
	v_cvt_pk_bf16_f32 v144, v232, v233
	v_exp_f32_e32 v219, v146
	s_waitcnt lgkmcnt(0)
	v_mfma_f32_32x32x16_bf16 v[64:79], v[170:173], v[116:119], v[64:79]
	ds_read_b128 v[170:173], v192 offset:40960
	v_add_f32_e32 v150, v219, v145
	v_cvt_pk_bf16_f32 v145, v228, v229
	v_cvt_pk_bf16_f32 v146, v230, v231
	v_exp_f32_e32 v236, v147
	s_waitcnt lgkmcnt(0)
	v_mfma_f32_32x32x16_bf16 v[80:95], v[170:173], v[116:119], v[80:95]
	ds_read_b128 v[170:173], v193 offset:32768
	v_add_f32_e32 v150, v236, v150
	v_cvt_pk_bf16_f32 v147, v153, v155
	v_permlane32_swap_b32_e32 v144, v146
	v_exp_f32_e32 v155, v148
	s_waitcnt lgkmcnt(0)
	v_mfma_f32_32x32x16_bf16 v[64:79], v[170:173], v[120:123], v[64:79]
	ds_read_b128 v[170:173], v193 offset:40960
	v_add_f32_e32 v150, v155, v150
	v_permlane32_swap_b32_e32 v145, v147
	v_cvt_pk_bf16_f32 v148, v209, v211
	v_exp_f32_e32 v209, v149
	s_waitcnt lgkmcnt(0)
; DEVI void mask_tile(f32x16& p0, f32x16& p1, bool nv16) {
; #pragma unroll
;   for (int r = 0; r < 16; ++r) { if (!(nv16 && r < 8)) p0[r] = -1e30f; p1[r] = -1e30f; }
; }
; DEVI void qkt(f32x16& p0, f32x16& p1, const char* Ks, const char* Rs, const bf16x8* qr, const char* Qrs, int r32, int hi) {
;   p0 = f32x16{}; p1 = f32x16{};
; #pragma unroll
;   for (int d0 = 0; d0 < 8; ++d0) { int cb = (d0 * 16 + hi * 8) * 2;
;     bf16x8 b0 = *reinterpret_cast<const bf16x8*>(Ks + KSWZ(r32, cb));
;     bf16x8 b1 = *reinterpret_cast<const bf16x8*>(Ks + KSWZ(32 + r32, cb));
;     p0 = __builtin_amdgcn_mfma_f32_32x32x16_bf16(b0, qr[d0], p0, 0, 0, 0);
;     p1 = __builtin_amdgcn_mfma_f32_32x32x16_bf16(b1, qr[d0], p1, 0, 0, 0); }
; #pragma unroll
;   for (int d0 = 0; d0 < 4; ++d0) { int cb = (d0 * 16 + hi * 8) * 2;
;     bf16x8 b0 = *reinterpret_cast<const bf16x8*>(Rs + RSWZ(r32, cb));
;     bf16x8 b1 = *reinterpret_cast<const bf16x8*>(Rs + RSWZ(32 + r32, cb));
;     bf16x8 qf = *reinterpret_cast<const bf16x8*>(Qrs + RSWZ(r32, cb));
;     p0 = __builtin_amdgcn_mfma_f32_32x32x16_bf16(b0, qf, p0, 0, 0, 0);
;     p1 = __builtin_amdgcn_mfma_f32_32x32x16_bf16(b1, qf, p1, 0, 0, 0); }
; }
; DEVI void pv_d0(f32x16* o, const char* Vs, int r32, int hi, bf16x8 pa0, bf16x8 pa1, bf16x8 pa2, bf16x8 pa3) {
; #pragma unroll
;   for (int d0 = 0; d0 < 4; ++d0) {
;     const bf16x8 f0 = *reinterpret_cast<const bf16x8*>(Vs + RSWZ(d0 * 32 + r32, (0 * 16 + hi * 8) * 2));
;     const bf16x8 f1 = *reinterpret_cast<const bf16x8*>(Vs + RSWZ(d0 * 32 + r32, (1 * 16 + hi * 8) * 2));
;     const bf16x8 f2 = *reinterpret_cast<const bf16x8*>(Vs + RSWZ(d0 * 32 + r32, (2 * 16 + hi * 8) * 2));
;     const bf16x8 f3 = *reinterpret_cast<const bf16x8*>(Vs + RSWZ(d0 * 32 + r32, (3 * 16 + hi * 8) * 2));
;     o[d0] = __builtin_amdgcn_mfma_f32_32x32x16_bf16(pa0, f0, o[d0], 0, 0, 0);
;     o[d0] = __builtin_amdgcn_mfma_f32_32x32x16_bf16(pa1, f1, o[d0], 0, 0, 0);
;     o[d0] = __builtin_amdgcn_mfma_f32_32x32x16_bf16(pa2, f2, o[d0], 0, 0, 0);
;     o[d0] = __builtin_amdgcn_mfma_f32_32x32x16_bf16(pa3, f3, o[d0], 0, 0, 0);
;   }
; }
	v_mfma_f32_32x32x16_bf16 v[80:95], v[170:173], v[120:123], v[80:95]
	ds_read_b128 v[170:173], v194 offset:32768
	v_add_f32_e32 v153, v209, v150
	v_cvt_pk_bf16_f32 v149, v212, v214
	v_cvt_pk_bf16_f32 v150, v210, v215
	v_exp_f32_e32 v210, v151
	s_waitcnt lgkmcnt(0)
	v_mfma_f32_32x32x16_bf16 v[64:79], v[170:173], v[124:127], v[64:79]
	ds_read_b128 v[170:173], v194 offset:40960
	v_add_f32_e32 v153, v210, v153
	v_cvt_pk_bf16_f32 v151, v217, v218
	v_permlane32_swap_b32_e32 v148, v150
	v_exp_f32_e32 v211, v152
	s_waitcnt lgkmcnt(0)
	v_mfma_f32_32x32x16_bf16 v[80:95], v[170:173], v[124:127], v[80:95]
	ds_read_b128 v[228:231], v195
	v_add_f32_e32 v170, v211, v153
	v_mov_b32_e32 v171, v170
	v_permlane32_swap_b32_e32 v149, v151
	ds_read_b128 v[232:235], v196
	v_permlane32_swap_b32_e32 v170, v171
	v_cvt_pk_bf16_f32 v152, v154, v216
	v_cvt_pk_bf16_f32 v153, v219, v236
	ds_read_b128 v[236:239], v225
	s_waitcnt lgkmcnt(0)
	v_mfma_f32_32x32x16_bf16 v[64:79], v[228:231], v[236:239], v[64:79]
	ds_read_b128 v[228:231], v197
	v_mfma_f32_32x32x16_bf16 v[80:95], v[232:235], v[236:239], v[80:95]
	ds_read_b128 v[240:243], v223
	ds_read_b128 v[232:235], v226
	ds_read_b128 v[236:239], v200
	s_waitcnt lgkmcnt(2)
	v_mfma_f32_32x32x16_bf16 v[64:79], v[228:231], v[240:243], v[64:79]
	ds_read_b128 v[228:231], v199
	ds_read_b128 v[244:247], v227
	s_waitcnt lgkmcnt(0)
	v_mfma_f32_32x32x16_bf16 v[64:79], v[228:231], v[244:247], v[64:79]
	ds_read_b128 v[228:231], v201
	s_waitcnt lgkmcnt(0)
	v_mfma_f32_32x32x16_bf16 v[64:79], v[228:231], v[232:235], v[64:79]
	ds_read_b128 v[226:229], v198
	s_waitcnt lgkmcnt(0)
	v_mfma_f32_32x32x16_bf16 v[80:95], v[226:229], v[240:243], v[80:95]
	ds_read_b128 v[240:243], v202
	v_cvt_pk_bf16_f32 v154, v155, v209
	v_cvt_pk_bf16_f32 v155, v210, v211
	s_nop 0
	v_permlane32_swap_b32_e32 v152, v154
	v_permlane32_swap_b32_e32 v153, v155
	v_mfma_f32_32x32x16_bf16 v[80:95], v[236:239], v[244:247], v[80:95]
	s_nop 1
	v_cndmask_b32_e32 v229, v72, v208, vcc
	v_cndmask_b32_e32 v227, v76, v208, vcc
	v_cndmask_b32_e32 v228, v73, v208, vcc
	s_waitcnt lgkmcnt(0)
	v_mfma_f32_32x32x16_bf16 v[80:95], v[240:243], v[232:235], v[80:95]
	s_nop 11
	v_cndmask_b32_e32 v73, v95, v208, vcc
	v_cndmask_b32_e32 v226, v74, v208, vcc
	v_cndmask_b32_e32 v172, v79, v208, vcc
	v_cndmask_b32_e32 v173, v78, v208, vcc
	v_cndmask_b32_e32 v223, v77, v208, vcc
	v_cndmask_b32_e32 v225, v75, v208, vcc
	v_cndmask_b32_e32 v72, v94, v208, vcc
	v_cndmask_b32_e32 v75, v93, v208, vcc
	v_cndmask_b32_e32 v74, v92, v208, vcc
	v_cndmask_b32_e32 v77, v91, v208, vcc
	v_cndmask_b32_e32 v76, v90, v208, vcc
	v_cndmask_b32_e32 v79, v89, v208, vcc
	v_cndmask_b32_e32 v78, v88, v208, vcc
	v_cndmask_b32_e32 v87, v87, v208, vcc
	v_cndmask_b32_e32 v86, v86, v208, vcc
	v_cndmask_b32_e32 v85, v85, v208, vcc
	v_cndmask_b32_e32 v84, v84, v208, vcc
	v_cndmask_b32_e32 v83, v83, v208, vcc
	v_cndmask_b32_e32 v82, v82, v208, vcc
	v_cndmask_b32_e32 v81, v81, v208, vcc
	v_cndmask_b32_e32 v80, v80, v208, vcc
	global_load_dwordx4 v[90:93], v162, s[36:37] offset:3456
	global_load_dwordx4 v[156:159], v164, s[36:37] offset:3456
	ds_read_b128 v[230:233], v177 offset:16384
	ds_read_b128 v[234:237], v161 offset:16384
	ds_read_b128 v[238:241], v180 offset:16384
	v_max_f32_e32 v88, v65, v65
	v_max_f32_e32 v89, v64, v64
	s_waitcnt lgkmcnt(2)
	v_mfma_f32_32x32x16_bf16 v[16:31], v[140:143], v[230:233], v[16:31]
	ds_read_b128 v[230:233], v177 offset:20480
	v_max_f32_e32 v88, v89, v88
	v_max3_f32 v88, v88, v66, v67
	v_max3_f32 v88, v88, v68, v69
	ds_read_b128 v[242:245], v179 offset:16384
	v_max3_f32 v88, v88, v70, v71
	v_max3_f32 v88, v88, v229, v228
	s_waitcnt lgkmcnt(1)
	v_mfma_f32_32x32x16_bf16 v[48:63], v[140:143], v[230:233], v[48:63]
	ds_read_b128 v[230:233], v177 offset:24576
	v_max3_f32 v88, v88, v226, v225
	v_max3_f32 v88, v88, v227, v223
	v_max3_f32 v88, v88, v173, v172
	v_max3_f32 v88, v88, v80, v81
	v_max3_f32 v88, v88, v82, v83
	v_max3_f32 v88, v88, v84, v85
	v_mfma_f32_32x32x16_bf16 v[16:31], v[144:147], v[234:237], v[16:31]
	ds_read_b128 v[234:237], v161 offset:20480
	v_max3_f32 v88, v88, v86, v87
	v_max3_f32 v88, v88, v78, v79
	v_max3_f32 v88, v88, v76, v77
	v_max3_f32 v88, v88, v74, v75
	v_max3_f32 v88, v88, v72, v73
	v_mov_b32_e32 v89, v88
	s_waitcnt lgkmcnt(1)
	v_mfma_f32_32x32x16_bf16 v[32:47], v[140:143], v[230:233], v[32:47]
	ds_read_b128 v[230:233], v177 offset:28672
	v_permlane32_swap_b32_e32 v88, v89
	v_max_f32_e32 v89, v89, v89
	v_max_f32_e32 v88, v88, v88
	v_max_f32_e32 v88, v88, v89
	v_sub_f32_e32 v89, v88, v222
	s_waitcnt lgkmcnt(1)
	v_mfma_f32_32x32x16_bf16 v[48:63], v[144:147], v[234:237], v[48:63]
	ds_read_b128 v[234:237], v161 offset:24576
	v_cmp_ge_f32_e32 vcc, s91, v89
	v_max_f32_e32 v89, v222, v222
	v_max_f32_e32 v89, v89, v88
	v_sub_f32_e32 v88, v222, v89
	v_mul_f32_e32 v88, 0x3dd53b94, v88
	v_exp_f32_e32 v88, v88
	s_waitcnt lgkmcnt(1)
	v_mfma_f32_32x32x16_bf16 v[0:15], v[140:143], v[230:233], v[0:15]
	s_cmp_eq_u64 vcc, exec
	s_cselect_b64 s[8:9], -1, 0
	v_cndmask_b32_e64 v88, v88, 1.0, s[8:9]
	v_cmp_gt_f32_e32 vcc, 1.0, v88
	v_mfma_f32_32x32x16_bf16 v[16:31], v[148:151], v[238:241], v[16:31]
	ds_read_b128 v[238:241], v180 offset:20480
	s_waitcnt lgkmcnt(1)
	v_mfma_f32_32x32x16_bf16 v[32:47], v[144:147], v[234:237], v[32:47]
	ds_read_b128 v[234:237], v161 offset:28672
	s_waitcnt lgkmcnt(1)
	v_mfma_f32_32x32x16_bf16 v[48:63], v[148:151], v[238:241], v[48:63]
	ds_read_b128 v[238:241], v180 offset:24576
	s_waitcnt lgkmcnt(1)
	v_mfma_f32_32x32x16_bf16 v[0:15], v[144:147], v[234:237], v[0:15]
	v_mfma_f32_32x32x16_bf16 v[16:31], v[152:155], v[242:245], v[16:31]
	ds_read_b128 v[242:245], v179 offset:20480
	s_waitcnt lgkmcnt(1)
	v_mfma_f32_32x32x16_bf16 v[32:47], v[148:151], v[238:241], v[32:47]
	ds_read_b128 v[238:241], v180 offset:28672
	s_waitcnt lgkmcnt(1)
	v_mfma_f32_32x32x16_bf16 v[48:63], v[152:155], v[242:245], v[48:63]
	ds_read_b128 v[242:245], v179 offset:24576
	s_waitcnt lgkmcnt(1)
	v_mfma_f32_32x32x16_bf16 v[0:15], v[148:151], v[238:241], v[0:15]
	s_waitcnt lgkmcnt(0)
	v_mfma_f32_32x32x16_bf16 v[32:47], v[152:155], v[242:245], v[32:47]
	ds_read_b128 v[242:245], v179 offset:28672
	s_waitcnt vmcnt(2)
	ds_write_b128 v184, v[128:131] offset:49152
	ds_write_b128 v184, v[132:135] offset:57344
	ds_write_b128 v203, v[136:139]
	s_waitcnt lgkmcnt(0)
	s_barrier
; #define SWRITE_KR(b) do { int kc = sc * 2; *(bf16x8*)(K_lds + (b) * SHM_K + KSWZ(sr, kc)) = ks0; *(bf16x8*)(K_lds + (b) * SHM_K + KSWZ(32 + sr, kc)) = ks1; \
;     *(bf16x8*)(R_lds + (b) * SHM_R + RSWZ(rr_, rc_ * 2)) = rs0; } while (0)
; #define SWRITE_V(b) do { *(bf16x8*)(V_lds + (b) * SHM_V + RSWZ(vd, vc * 16)) = vs0; *(bf16x8*)(V_lds + (b) * SHM_V + RSWZ(vd + 64, vc * 16)) = vs1; } while (0)
; #define SWAIT() asm volatile("s_waitcnt vmcnt(0)" ::: "memory")
; #define RESC(a) do { if (__any((a) < 1.f)) { if (hi == 0) al_l[r32] = (a); asm volatile("s_waitcnt lgkmcnt(0)" ::: "memory"); \
;     _Pragma("unroll") for (int d = 0; d < 4; ++d) _Pragma("unroll") for (int r = 0; r < 16; ++r) o[d][r] *= al_l[crow(r, hi)]; } } while (0)
; DEVI void attn_item(const u16* __restrict__ Qb, const u16* __restrict__ KNh, const u16* __restrict__ VTh, int Lpad, const u16* __restrict__ KRb,
;                     const u16* __restrict__ SZb, u16* __restrict__ AOb, int NT, char* lds, const int wid_s_) {
;     ...
;     pv_d0(o, V_lds + SHM_V, r32, hi, pa0, pa1, pa2, pa3); partialSM(pA0, pA1, m_reg, mnA, alA);
;     SWRITE_KR(1);
;     __syncthreads(); SWAIT(); SWRITE_V(1);
;     RESC(alA); __syncthreads();
;   }
	v_mfma_f32_32x32x16_bf16 v[0:15], v[152:155], v[242:245], v[0:15]
	s_waitcnt vmcnt(0)
	ds_write_b128 v185, v[90:93] offset:16384
	ds_write_b128 v185, v[156:159] offset:24576
	s_cbranch_vccz .LBB0_989
	s_and_saveexec_b64 s[14:15], s[6:7]
	ds_write_b32 v181, v88 offset:128
	s_or_b64 exec, exec, s[14:15]
	s_waitcnt lgkmcnt(0)
	v_add_u32_e32 v94, v178, v160
	ds_read_b128 v[90:93], v94 offset:224
	ds_read_b128 v[128:131], v94 offset:192
	ds_read_b128 v[132:135], v94 offset:160
	ds_read_b128 v[136:139], v94 offset:128
	s_waitcnt lgkmcnt(3)
	v_pk_mul_f32 v[28:29], v[28:29], v[90:91]
	s_waitcnt lgkmcnt(2)
	v_pk_mul_f32 v[24:25], v[24:25], v[128:129]
	s_waitcnt lgkmcnt(1)
	v_pk_mul_f32 v[20:21], v[20:21], v[132:133]
	v_pk_mul_f32 v[30:31], v[30:31], v[92:93]
	v_pk_mul_f32 v[26:27], v[26:27], v[130:131]
	v_pk_mul_f32 v[22:23], v[22:23], v[134:135]
	s_waitcnt lgkmcnt(0)
	v_pk_mul_f32 v[18:19], v[18:19], v[138:139]
	v_pk_mul_f32 v[16:17], v[16:17], v[136:137]
	v_pk_mul_f32 v[60:61], v[60:61], v[90:91]
	v_pk_mul_f32 v[56:57], v[56:57], v[128:129]
	v_pk_mul_f32 v[52:53], v[52:53], v[132:133]
	v_pk_mul_f32 v[62:63], v[62:63], v[92:93]
	v_pk_mul_f32 v[58:59], v[58:59], v[130:131]
	v_pk_mul_f32 v[54:55], v[54:55], v[134:135]
	v_pk_mul_f32 v[50:51], v[50:51], v[138:139]
	v_pk_mul_f32 v[48:49], v[48:49], v[136:137]
	v_pk_mul_f32 v[44:45], v[44:45], v[90:91]
	v_pk_mul_f32 v[40:41], v[40:41], v[128:129]
	v_pk_mul_f32 v[36:37], v[36:37], v[132:133]
	v_pk_mul_f32 v[46:47], v[46:47], v[92:93]
	v_pk_mul_f32 v[42:43], v[42:43], v[130:131]
	v_pk_mul_f32 v[38:39], v[38:39], v[134:135]
	v_pk_mul_f32 v[34:35], v[34:35], v[138:139]
	v_pk_mul_f32 v[32:33], v[32:33], v[136:137]
	v_pk_mul_f32 v[12:13], v[12:13], v[90:91]
	v_pk_mul_f32 v[8:9], v[8:9], v[128:129]
	v_pk_mul_f32 v[4:5], v[4:5], v[132:133]
	v_pk_mul_f32 v[14:15], v[14:15], v[92:93]
	v_pk_mul_f32 v[10:11], v[10:11], v[130:131]
	v_pk_mul_f32 v[6:7], v[6:7], v[134:135]
	v_pk_mul_f32 v[2:3], v[2:3], v[138:139]
	v_pk_mul_f32 v[0:1], v[0:1], v[136:137]
.LBB0_989:
	v_cndmask_b32_e64 v222, v89, v222, s[8:9]
	v_mul_f32_e32 v90, 0xbdd53b94, v222
	v_mov_b32_e32 v129, v90
	v_fmamk_f32 v64, v64, 0x3dd53b94, v90
	v_fmamk_f32 v65, v65, 0x3dd53b94, v90
	v_fmamk_f32 v66, v66, 0x3dd53b94, v90
	v_fmamk_f32 v67, v67, 0x3dd53b94, v90
	v_fmamk_f32 v68, v68, 0x3dd53b94, v90
	v_fmamk_f32 v69, v69, 0x3dd53b94, v90
	v_fmamk_f32 v70, v70, 0x3dd53b94, v90
	v_fmamk_f32 v71, v71, 0x3dd53b94, v90
	v_fmamk_f32 v89, v229, 0x3dd53b94, v90
	v_fmamk_f32 v91, v228, 0x3dd53b94, v90
	v_fmamk_f32 v92, v226, 0x3dd53b94, v90
	v_fmamk_f32 v93, v225, 0x3dd53b94, v90
	v_fmamk_f32 v94, v227, 0x3dd53b94, v90
	v_fmamk_f32 v95, v223, 0x3dd53b94, v90
	v_fmamk_f32 v128, v173, 0x3dd53b94, v90
	v_fmac_f32_e32 v129, 0x3dd53b94, v172
	v_exp_f32_e32 v231, v64
	v_exp_f32_e32 v235, v65
	v_exp_f32_e32 v230, v66
	v_exp_f32_e32 v232, v67
	v_exp_f32_e32 v233, v68
	v_exp_f32_e32 v236, v69
	v_exp_f32_e32 v234, v70
	v_exp_f32_e32 v237, v71
	v_exp_f32_e32 v156, v89
	v_exp_f32_e32 v157, v91
	v_exp_f32_e32 v158, v92
	v_exp_f32_e32 v159, v93
	v_exp_f32_e32 v228, v94
	v_exp_f32_e32 v229, v95
	v_exp_f32_e32 v154, v128
	v_exp_f32_e32 v155, v129
	v_add_f32_e32 v64, v204, v221
	v_fmac_f32_e32 v64, v220, v182
	v_add_f32_e32 v182, v170, v171
	v_add_u32_e32 v166, 0x4000, v166
	s_add_i32 s1, s2, 2
	v_pk_fma_f32 v[80:81], v[80:81], s[80:81], v[90:91] op_sel_hi:[1,0,0]
	v_pk_fma_f32 v[152:153], v[82:83], s[80:81], v[90:91] op_sel_hi:[1,0,0]
	v_pk_fma_f32 v[150:151], v[84:85], s[80:81], v[90:91] op_sel_hi:[1,0,0]
	v_pk_fma_f32 v[148:149], v[86:87], s[80:81], v[90:91] op_sel_hi:[1,0,0]
	v_pk_fma_f32 v[142:143], v[78:79], s[80:81], v[90:91] op_sel_hi:[1,0,0]
	v_pk_fma_f32 v[146:147], v[76:77], s[80:81], v[90:91] op_sel_hi:[1,0,0]
	v_pk_fma_f32 v[140:141], v[74:75], s[80:81], v[90:91] op_sel_hi:[1,0,0]
	v_pk_fma_f32 v[144:145], v[72:73], s[80:81], v[90:91] op_sel_hi:[1,0,0]
	v_fmac_f32_e32 v182, v64, v224
	v_add_u32_e32 v162, s82, v162
	v_add_u32_e32 v164, s82, v164
	s_cmp_ge_u32 s2, s4
	v_add_u32_e32 v168, 0x80000, v168
	s_waitcnt lgkmcnt(0)
	s_barrier
	s_cbranch_scc1 .LBB0_991
	s_mov_b32 s2, s1
	v_mov_b32_e32 v220, v88
	s_branch .LBB0_981
